# fused norm: the residual stores are deferred behind the row-sum exchange (waves 4-7 issue theirs before it, waves 0-3 after), so the exchange no longer waits for the residual tile to drain
# speedup vs baseline: 1.0230x; 1.0170x over previous
.LBB0_182:
	s_add_i32 s91, s2, 2
	s_add_u32 s12, s34, 0x80
	s_addc_u32 s3, s35, 0
	s_add_i32 s13, 0, 0x10000
	v_add_u32_e32 v142, s13, v183
	ds_read_b128 v[130:133], v142
	ds_read_b128 v[134:137], v142 offset:1024
	ds_read_b128 v[138:141], v142 offset:2048
	ds_read_b128 v[142:145], v142 offset:3072
	s_cmp_eq_u32 s88, s2
	s_cselect_b32 s2, s0, s12
	s_cselect_b32 s3, s1, s3
	s_cselect_b32 s43, s41, s90
	s_cselect_b32 s42, s40, s89
	v_lshl_add_u64 v[190:191], s[34:35], 0, v[174:175]
	s_add_i32 m0, s55, 0xc000
	ds_read_b128 v[146:149], v184
	ds_read_b128 v[150:153], v184 offset:1024
	ds_read_b128 v[154:157], v184 offset:2048
	ds_read_b128 v[158:161], v184 offset:3072
	ds_read_b128 v[162:165], v184 offset:4096
	ds_read_b128 v[166:169], v184 offset:5120
	ds_read_b128 v[178:181], v184 offset:6144
	ds_read_b128 v[186:189], v184 offset:7168
	global_load_lds_dwordx4 v[190:191], off
	v_lshl_add_u64 v[190:191], s[34:35], 0, v[176:177]
	s_add_i32 m0, s55, 0xe000
	s_nop 0
	global_load_lds_dwordx4 v[190:191], off
	s_waitcnt lgkmcnt(8)
	s_barrier
	s_waitcnt lgkmcnt(0)
	s_waitcnt lgkmcnt(0)
	v_mfma_f32_16x16x32_bf16 v[126:129], v[130:133], v[146:149], v[126:129]
	v_mfma_f32_16x16x32_bf16 v[122:125], v[138:141], v[146:149], v[122:125]
	v_mfma_f32_16x16x32_bf16 v[118:121], v[130:133], v[154:157], v[118:121]
	v_mfma_f32_16x16x32_bf16 v[114:117], v[138:141], v[154:157], v[114:117]
	v_mfma_f32_16x16x32_bf16 v[110:113], v[130:133], v[162:165], v[110:113]
	v_mfma_f32_16x16x32_bf16 v[106:109], v[138:141], v[162:165], v[106:109]
	v_mfma_f32_16x16x32_bf16 v[102:105], v[130:133], v[178:181], v[102:105]
	v_mfma_f32_16x16x32_bf16 v[98:101], v[138:141], v[178:181], v[98:101]
	v_mfma_f32_16x16x32_bf16 v[126:129], v[134:137], v[150:153], v[126:129]
	v_mfma_f32_16x16x32_bf16 v[122:125], v[142:145], v[150:153], v[122:125]
	v_mfma_f32_16x16x32_bf16 v[118:121], v[134:137], v[158:161], v[118:121]
	v_mfma_f32_16x16x32_bf16 v[114:117], v[142:145], v[158:161], v[114:117]
	v_mfma_f32_16x16x32_bf16 v[110:113], v[134:137], v[166:169], v[110:113]
	v_mfma_f32_16x16x32_bf16 v[106:109], v[142:145], v[166:169], v[106:109]
	v_mfma_f32_16x16x32_bf16 v[102:105], v[134:137], v[186:189], v[102:105]
	v_mfma_f32_16x16x32_bf16 v[98:101], v[142:145], v[186:189], v[98:101]
	s_barrier
	s_add_i32 s92, 0, 0x14000
	s_add_i32 s12, s13, s54
	v_add_u32_e32 v185, s92, v183
	v_lshl_add_u64 v[230:231], s[42:43], 0, v[170:171]
	s_mov_b32 m0, s12
	ds_read_b128 v[190:193], v185
	ds_read_b128 v[194:197], v185 offset:1024
	ds_read_b128 v[198:201], v185 offset:2048
	ds_read_b128 v[226:229], v185 offset:3072
	global_load_lds_dwordx4 v[230:231], off
	v_lshl_add_u64 v[232:233], s[42:43], 0, v[172:173]
	s_add_i32 m0, s12, 0x2000
	s_nop 0
	global_load_lds_dwordx4 v[232:233], off
	s_barrier
	s_waitcnt lgkmcnt(0)
	s_waitcnt lgkmcnt(0)
	v_mfma_f32_16x16x32_bf16 v[62:65], v[190:193], v[146:149], v[62:65]
	v_mfma_f32_16x16x32_bf16 v[58:61], v[198:201], v[146:149], v[58:61]
	v_mfma_f32_16x16x32_bf16 v[54:57], v[190:193], v[154:157], v[54:57]
	v_mfma_f32_16x16x32_bf16 v[50:53], v[198:201], v[154:157], v[50:53]
	v_mfma_f32_16x16x32_bf16 v[46:49], v[190:193], v[162:165], v[46:49]
	v_mfma_f32_16x16x32_bf16 v[42:45], v[198:201], v[162:165], v[42:45]
	v_mfma_f32_16x16x32_bf16 v[38:41], v[190:193], v[178:181], v[38:41]
	v_mfma_f32_16x16x32_bf16 v[34:37], v[198:201], v[178:181], v[34:37]
	v_mfma_f32_16x16x32_bf16 v[62:65], v[194:197], v[150:153], v[62:65]
	v_mfma_f32_16x16x32_bf16 v[58:61], v[226:229], v[150:153], v[58:61]
	v_mfma_f32_16x16x32_bf16 v[54:57], v[194:197], v[158:161], v[54:57]
	v_mfma_f32_16x16x32_bf16 v[50:53], v[226:229], v[158:161], v[50:53]
	v_mfma_f32_16x16x32_bf16 v[46:49], v[194:197], v[166:169], v[46:49]
	v_mfma_f32_16x16x32_bf16 v[42:45], v[226:229], v[166:169], v[42:45]
	v_mfma_f32_16x16x32_bf16 v[38:41], v[194:197], v[186:189], v[38:41]
	v_mfma_f32_16x16x32_bf16 v[34:37], v[226:229], v[186:189], v[34:37]
	s_mov_b32 m0, s55
	v_lshl_add_u64 v[234:235], s[2:3], 0, v[170:171]
	s_barrier
	ds_read_b128 v[146:149], v184 offset:16384
	ds_read_b128 v[150:153], v184 offset:17408
	ds_read_b128 v[154:157], v184 offset:18432
	ds_read_b128 v[158:161], v184 offset:19456
	ds_read_b128 v[162:165], v184 offset:20480
	ds_read_b128 v[166:169], v184 offset:21504
	ds_read_b128 v[178:181], v184 offset:22528
	ds_read_b128 v[186:189], v184 offset:23552
	global_load_lds_dwordx4 v[234:235], off
	v_lshl_add_u64 v[236:237], s[2:3], 0, v[172:173]
	s_mov_b32 m0, s58
	s_nop 0
	global_load_lds_dwordx4 v[236:237], off
	s_barrier
	s_waitcnt lgkmcnt(0)
	s_waitcnt lgkmcnt(0)
	v_mfma_f32_16x16x32_bf16 v[94:97], v[130:133], v[146:149], v[94:97]
	v_mfma_f32_16x16x32_bf16 v[90:93], v[138:141], v[146:149], v[90:93]
	v_mfma_f32_16x16x32_bf16 v[86:89], v[130:133], v[154:157], v[86:89]
	v_mfma_f32_16x16x32_bf16 v[82:85], v[138:141], v[154:157], v[82:85]
	v_mfma_f32_16x16x32_bf16 v[78:81], v[130:133], v[162:165], v[78:81]
	v_mfma_f32_16x16x32_bf16 v[74:77], v[138:141], v[162:165], v[74:77]
	v_mfma_f32_16x16x32_bf16 v[70:73], v[130:133], v[178:181], v[70:73]
	v_mfma_f32_16x16x32_bf16 v[66:69], v[138:141], v[178:181], v[66:69]
	v_mfma_f32_16x16x32_bf16 v[94:97], v[134:137], v[150:153], v[94:97]
	v_mfma_f32_16x16x32_bf16 v[90:93], v[142:145], v[150:153], v[90:93]
	v_mfma_f32_16x16x32_bf16 v[86:89], v[134:137], v[158:161], v[86:89]
	v_mfma_f32_16x16x32_bf16 v[82:85], v[142:145], v[158:161], v[82:85]
	v_mfma_f32_16x16x32_bf16 v[78:81], v[134:137], v[166:169], v[78:81]
	v_mfma_f32_16x16x32_bf16 v[74:77], v[142:145], v[166:169], v[74:77]
	v_mfma_f32_16x16x32_bf16 v[70:73], v[134:137], v[186:189], v[70:73]
	v_mfma_f32_16x16x32_bf16 v[66:69], v[142:145], v[186:189], v[66:69]
	s_barrier
	s_add_u32 s12, s42, s18
	s_addc_u32 s13, s43, 0
	s_add_i32 s42, s92, s54
	v_lshl_add_u64 v[242:243], s[12:13], 0, v[170:171]
	s_mov_b32 m0, s42
	v_lshl_add_u64 v[244:245], s[12:13], 0, v[172:173]
	global_load_lds_dwordx4 v[242:243], off
	s_add_i32 m0, s42, 0x2000
	s_nop 0
	global_load_lds_dwordx4 v[244:245], off
	s_waitcnt vmcnt(6)
	s_barrier
	v_mfma_f32_16x16x32_bf16 v[30:33], v[190:193], v[146:149], v[30:33]
	v_mfma_f32_16x16x32_bf16 v[26:29], v[198:201], v[146:149], v[26:29]
	v_mfma_f32_16x16x32_bf16 v[22:25], v[190:193], v[154:157], v[22:25]
	v_mfma_f32_16x16x32_bf16 v[18:21], v[198:201], v[154:157], v[18:21]
	v_mfma_f32_16x16x32_bf16 v[14:17], v[190:193], v[162:165], v[14:17]
	v_mfma_f32_16x16x32_bf16 v[10:13], v[198:201], v[162:165], v[10:13]
	v_mfma_f32_16x16x32_bf16 v[6:9], v[190:193], v[178:181], v[6:9]
	v_mfma_f32_16x16x32_bf16 v[2:5], v[198:201], v[178:181], v[2:5]
	v_mfma_f32_16x16x32_bf16 v[30:33], v[194:197], v[150:153], v[30:33]
	v_mfma_f32_16x16x32_bf16 v[26:29], v[226:229], v[150:153], v[26:29]
	v_mfma_f32_16x16x32_bf16 v[22:25], v[194:197], v[158:161], v[22:25]
	v_mfma_f32_16x16x32_bf16 v[18:21], v[226:229], v[158:161], v[18:21]
	v_mfma_f32_16x16x32_bf16 v[14:17], v[194:197], v[166:169], v[14:17]
	v_mfma_f32_16x16x32_bf16 v[10:13], v[226:229], v[166:169], v[10:13]
	v_mfma_f32_16x16x32_bf16 v[6:9], v[194:197], v[186:189], v[6:9]
	v_mfma_f32_16x16x32_bf16 v[2:5], v[226:229], v[186:189], v[2:5]
	s_add_i32 s12, 0, 0x18000
	v_add_u32_e32 v142, s12, v183
	s_barrier
	ds_read_b128 v[130:133], v142
	ds_read_b128 v[134:137], v142 offset:1024
	ds_read_b128 v[138:141], v142 offset:2048
	ds_read_b128 v[142:145], v142 offset:3072
	s_add_u32 s2, s2, s18
	s_addc_u32 s3, s3, 0
	s_mov_b32 m0, s59
	v_lshl_add_u64 v[190:191], s[2:3], 0, v[170:171]
	ds_read_b128 v[146:149], v184 offset:32768
	ds_read_b128 v[150:153], v184 offset:33792
	ds_read_b128 v[154:157], v184 offset:34816
	ds_read_b128 v[158:161], v184 offset:35840
	ds_read_b128 v[162:165], v184 offset:36864
	ds_read_b128 v[166:169], v184 offset:37888
	ds_read_b128 v[178:181], v184 offset:38912
	ds_read_b128 v[186:189], v184 offset:39936
	global_load_lds_dwordx4 v[190:191], off
	v_lshl_add_u64 v[190:191], s[2:3], 0, v[172:173]
	s_mov_b32 m0, s77
	s_nop 0
	global_load_lds_dwordx4 v[190:191], off
	s_waitcnt lgkmcnt(8)
	s_barrier
	s_waitcnt lgkmcnt(0)
	s_waitcnt lgkmcnt(0)
	v_mfma_f32_16x16x32_bf16 v[126:129], v[130:133], v[146:149], v[126:129]
	v_mfma_f32_16x16x32_bf16 v[122:125], v[138:141], v[146:149], v[122:125]
	v_mfma_f32_16x16x32_bf16 v[118:121], v[130:133], v[154:157], v[118:121]
	v_mfma_f32_16x16x32_bf16 v[114:117], v[138:141], v[154:157], v[114:117]
	v_mfma_f32_16x16x32_bf16 v[110:113], v[130:133], v[162:165], v[110:113]
	v_mfma_f32_16x16x32_bf16 v[106:109], v[138:141], v[162:165], v[106:109]
	v_mfma_f32_16x16x32_bf16 v[102:105], v[130:133], v[178:181], v[102:105]
	v_mfma_f32_16x16x32_bf16 v[98:101], v[138:141], v[178:181], v[98:101]
	v_mfma_f32_16x16x32_bf16 v[126:129], v[134:137], v[150:153], v[126:129]
	v_mfma_f32_16x16x32_bf16 v[122:125], v[142:145], v[150:153], v[122:125]
	v_mfma_f32_16x16x32_bf16 v[118:121], v[134:137], v[158:161], v[118:121]
	v_mfma_f32_16x16x32_bf16 v[114:117], v[142:145], v[158:161], v[114:117]
	v_mfma_f32_16x16x32_bf16 v[110:113], v[134:137], v[166:169], v[110:113]
	v_mfma_f32_16x16x32_bf16 v[106:109], v[142:145], v[166:169], v[106:109]
	v_mfma_f32_16x16x32_bf16 v[102:105], v[134:137], v[186:189], v[102:105]
	v_mfma_f32_16x16x32_bf16 v[98:101], v[142:145], v[186:189], v[98:101]
	s_barrier
	s_add_i32 s2, 0, 0x1c000
	s_add_i32 s3, s12, s54
	v_add_u32_e32 v185, s2, v183
	v_lshl_add_u64 v[230:231], v[230:231], 0, s[20:21]
	s_mov_b32 m0, s3
	ds_read_b128 v[190:193], v185
	ds_read_b128 v[194:197], v185 offset:1024
	ds_read_b128 v[198:201], v185 offset:2048
	ds_read_b128 v[226:229], v185 offset:3072
	global_load_lds_dwordx4 v[230:231], off
	v_lshl_add_u64 v[230:231], v[232:233], 0, s[20:21]
	s_add_i32 m0, s3, 0x2000
	s_nop 0
	global_load_lds_dwordx4 v[230:231], off
	s_barrier
	s_waitcnt lgkmcnt(0)
	s_waitcnt lgkmcnt(0)
	v_mfma_f32_16x16x32_bf16 v[62:65], v[190:193], v[146:149], v[62:65]
	v_mfma_f32_16x16x32_bf16 v[58:61], v[198:201], v[146:149], v[58:61]
	v_mfma_f32_16x16x32_bf16 v[54:57], v[190:193], v[154:157], v[54:57]
	v_mfma_f32_16x16x32_bf16 v[50:53], v[198:201], v[154:157], v[50:53]
	v_mfma_f32_16x16x32_bf16 v[46:49], v[190:193], v[162:165], v[46:49]
	v_mfma_f32_16x16x32_bf16 v[42:45], v[198:201], v[162:165], v[42:45]
	v_mfma_f32_16x16x32_bf16 v[38:41], v[190:193], v[178:181], v[38:41]
	v_mfma_f32_16x16x32_bf16 v[34:37], v[198:201], v[178:181], v[34:37]
	v_mfma_f32_16x16x32_bf16 v[62:65], v[194:197], v[150:153], v[62:65]
	v_mfma_f32_16x16x32_bf16 v[58:61], v[226:229], v[150:153], v[58:61]
	v_mfma_f32_16x16x32_bf16 v[54:57], v[194:197], v[158:161], v[54:57]
	v_mfma_f32_16x16x32_bf16 v[50:53], v[226:229], v[158:161], v[50:53]
	v_mfma_f32_16x16x32_bf16 v[46:49], v[194:197], v[166:169], v[46:49]
	v_mfma_f32_16x16x32_bf16 v[42:45], v[226:229], v[166:169], v[42:45]
	v_mfma_f32_16x16x32_bf16 v[38:41], v[194:197], v[186:189], v[38:41]
	v_mfma_f32_16x16x32_bf16 v[34:37], v[226:229], v[186:189], v[34:37]
	s_mov_b32 m0, s80
	v_lshl_add_u64 v[230:231], v[234:235], 0, s[20:21]
	s_barrier
	ds_read_b128 v[146:149], v184 offset:49152
	ds_read_b128 v[150:153], v184 offset:50176
	ds_read_b128 v[154:157], v184 offset:51200
	ds_read_b128 v[158:161], v184 offset:52224
	ds_read_b128 v[162:165], v184 offset:53248
	ds_read_b128 v[166:169], v184 offset:54272
	ds_read_b128 v[178:181], v184 offset:55296
	ds_read_b128 v[186:189], v184 offset:56320
	global_load_lds_dwordx4 v[230:231], off
	v_lshl_add_u64 v[230:231], v[236:237], 0, s[20:21]
	s_mov_b32 m0, s81
	s_nop 0
	global_load_lds_dwordx4 v[230:231], off
	s_barrier
	s_waitcnt lgkmcnt(0)
	s_waitcnt lgkmcnt(0)
	v_mfma_f32_16x16x32_bf16 v[94:97], v[130:133], v[146:149], v[94:97]
	v_mfma_f32_16x16x32_bf16 v[90:93], v[138:141], v[146:149], v[90:93]
	v_mfma_f32_16x16x32_bf16 v[86:89], v[130:133], v[154:157], v[86:89]
	v_mfma_f32_16x16x32_bf16 v[82:85], v[138:141], v[154:157], v[82:85]
	v_mfma_f32_16x16x32_bf16 v[78:81], v[130:133], v[162:165], v[78:81]
	v_mfma_f32_16x16x32_bf16 v[74:77], v[138:141], v[162:165], v[74:77]
	v_mfma_f32_16x16x32_bf16 v[70:73], v[130:133], v[178:181], v[70:73]
	v_mfma_f32_16x16x32_bf16 v[66:69], v[138:141], v[178:181], v[66:69]
	v_mfma_f32_16x16x32_bf16 v[94:97], v[134:137], v[150:153], v[94:97]
	v_mfma_f32_16x16x32_bf16 v[90:93], v[142:145], v[150:153], v[90:93]
	v_mfma_f32_16x16x32_bf16 v[86:89], v[134:137], v[158:161], v[86:89]
	v_mfma_f32_16x16x32_bf16 v[82:85], v[142:145], v[158:161], v[82:85]
	v_mfma_f32_16x16x32_bf16 v[78:81], v[134:137], v[166:169], v[78:81]
	v_mfma_f32_16x16x32_bf16 v[74:77], v[142:145], v[166:169], v[74:77]
	v_mfma_f32_16x16x32_bf16 v[70:73], v[134:137], v[186:189], v[70:73]
	v_mfma_f32_16x16x32_bf16 v[66:69], v[142:145], v[186:189], v[66:69]
	s_barrier
	s_add_i32 s2, s2, s54
	v_lshl_add_u64 v[130:131], v[242:243], 0, s[20:21]
	s_mov_b32 m0, s2
	s_nop 0
	global_load_lds_dwordx4 v[130:131], off
	v_lshl_add_u64 v[130:131], v[244:245], 0, s[20:21]
	s_add_i32 m0, s2, 0x2000
	s_nop 0
	global_load_lds_dwordx4 v[130:131], off
	s_waitcnt vmcnt(6)
	s_barrier
	v_mfma_f32_16x16x32_bf16 v[30:33], v[190:193], v[146:149], v[30:33]
	v_mfma_f32_16x16x32_bf16 v[26:29], v[198:201], v[146:149], v[26:29]
	v_mfma_f32_16x16x32_bf16 v[22:25], v[190:193], v[154:157], v[22:25]
	v_mfma_f32_16x16x32_bf16 v[18:21], v[198:201], v[154:157], v[18:21]
	v_mfma_f32_16x16x32_bf16 v[14:17], v[190:193], v[162:165], v[14:17]
	v_mfma_f32_16x16x32_bf16 v[10:13], v[198:201], v[162:165], v[10:13]
	v_mfma_f32_16x16x32_bf16 v[6:9], v[190:193], v[178:181], v[6:9]
	v_mfma_f32_16x16x32_bf16 v[2:5], v[198:201], v[178:181], v[2:5]
	v_mfma_f32_16x16x32_bf16 v[30:33], v[194:197], v[150:153], v[30:33]
	v_mfma_f32_16x16x32_bf16 v[26:29], v[226:229], v[150:153], v[26:29]
	v_mfma_f32_16x16x32_bf16 v[22:25], v[194:197], v[158:161], v[22:25]
	v_mfma_f32_16x16x32_bf16 v[18:21], v[226:229], v[158:161], v[18:21]
	v_mfma_f32_16x16x32_bf16 v[14:17], v[194:197], v[166:169], v[14:17]
	v_mfma_f32_16x16x32_bf16 v[10:13], v[226:229], v[166:169], v[10:13]
	v_mfma_f32_16x16x32_bf16 v[6:9], v[194:197], v[186:189], v[6:9]
	v_mfma_f32_16x16x32_bf16 v[2:5], v[226:229], v[186:189], v[2:5]
	s_add_u32 s34, s34, 0x100
	s_addc_u32 s35, s35, 0
	s_add_u32 s89, s89, 0x100
	s_addc_u32 s90, s90, 0
	s_cmp_ge_i32 s91, s44
	s_mov_b32 s2, s91
	s_barrier
	s_cbranch_scc0 .LBB0_182
	s_cmp_lt_i32 s86, 64
	s_cselect_b64 s[34:35], -1, 0
	s_ashr_i32 s2, s45, 8
	s_ashr_i32 s3, s2, 31
	s_lshl_b64 s[2:3], s[2:3], 18
	s_add_u32 s2, s2, 0x3232000
	s_addc_u32 s3, s3, 0
	s_cmp_gt_i32 s86, 63
	s_cselect_b32 s12, 0x6000, 0
	s_cselect_b32 s45, s3, 0
	s_cselect_b32 s44, s2, 0
	s_add_u32 s12, s78, s12
	s_addc_u32 s13, s79, 0
	s_lshl_b32 s2, s87, 8
	s_ashr_i32 s3, s2, 31
	s_lshl_b64 s[2:3], s[2:3], 2
	s_add_u32 s12, s12, s2
	s_addc_u32 s13, s13, s3
	v_readlane_b32 s88, v254, 38
	s_add_u32 s42, s12, s88
	s_addc_u32 s43, s13, 0
	global_load_dwordx4 v[134:137], v0, s[42:43]
	global_load_dwordx4 v[130:133], v0, s[42:43] offset:64
	v_lshl_add_u32 v138, s86, 8, v182
	v_ashrrev_i32_e32 v139, 31, v138
	v_readlane_b32 s12, v252, 5
	v_lshlrev_b64 v[138:139], 12, v[138:139]
	v_readlane_b32 s13, v252, 6
	v_readlane_b32 s89, v254, 39
	s_and_b64 vcc, exec, s[34:35]
	v_lshl_add_u64 v[138:139], s[12:13], 0, v[138:139]
	v_lshl_add_u64 v[138:139], v[138:139], 0, s[2:3]
	v_lshl_add_u64 v[138:139], v[138:139], 0, s[88:89]
	v_lshl_add_u64 v[178:179], v[138:139], 0, v[0:1]
	v_lshl_add_u64 v[180:181], v[178:179], 0, s[22:23]
	v_readfirstlane_b32 s88, v178
	v_readfirstlane_b32 s89, v179
	v_and_b32_e32 v178, 15, v202
	v_bfe_u32 v179, v202, 4, 2
	v_lshlrev_b32_e32 v178, 12, v178
	v_lshl_or_b32 v178, v179, 4, v178
	s_mov_b32 s13, 0
	s_and_b64 vcc, exec, s[34:35]
	s_cbranch_vccz .Lre_nf
	v_readlane_b32 s2, v252, 2
	v_readlane_b32 s3, v255, 14
	v_readlane_b32 s12, v255, 12
	s_cmp_eq_u32 s2, 0x100
	s_cbranch_scc0 .Lre_nf
	s_cmp_eq_u32 s3, 5
	s_cbranch_scc1 .Lre_f
	s_cmp_eq_u32 s3, 8
	s_cbranch_scc0 .Lre_nf
	s_cmp_lt_u32 s12, 3
	s_cbranch_scc0 .Lre_nf
.Lre_f:
	s_mov_b32 s13, 1
.Lre_nf:
	s_and_b64 vcc, exec, s[34:35]
	s_cbranch_vccz .Lre0_split
	s_add_u32 s2, s88, s22
	s_addc_u32 s3, s89, s23
	s_nop 1
	global_load_dwordx4 v[138:141], v178, s[2:3] offset:0
	global_load_dwordx4 v[142:145], v178, s[2:3] offset:64
	s_add_u32 s2, s2, 0x10000
	s_addc_u32 s3, s3, 0
	global_load_dwordx4 v[146:149], v178, s[2:3] offset:0
	global_load_dwordx4 v[150:153], v178, s[2:3] offset:64
	s_add_u32 s2, s2, 0x10000
	s_addc_u32 s3, s3, 0
	global_load_dwordx4 v[154:157], v178, s[2:3] offset:0
	global_load_dwordx4 v[158:161], v178, s[2:3] offset:64
	s_add_u32 s2, s2, 0x10000
	s_addc_u32 s3, s3, 0
	global_load_dwordx4 v[162:165], v178, s[2:3] offset:0
	global_load_dwordx4 v[166:169], v178, s[2:3] offset:64
	s_add_u32 s2, s2, 0x50000
	s_addc_u32 s3, s3, 0
	global_load_dwordx4 v[186:189], v178, s[2:3] offset:0
	global_load_dwordx4 v[190:193], v178, s[2:3] offset:64
	s_add_u32 s2, s2, 0x10000
	s_addc_u32 s3, s3, 0
	global_load_dwordx4 v[194:197], v178, s[2:3] offset:0
	global_load_dwordx4 v[198:201], v178, s[2:3] offset:64
	s_add_u32 s2, s2, 0x10000
	s_addc_u32 s3, s3, 0
	global_load_dwordx4 v[226:229], v178, s[2:3] offset:0
	global_load_dwordx4 v[230:233], v178, s[2:3] offset:64
	s_add_u32 s2, s2, 0x10000
	s_addc_u32 s3, s3, 0
	global_load_dwordx4 v[234:237], v178, s[2:3] offset:0
	global_load_dwordx4 v[242:245], v178, s[2:3] offset:64
	s_mov_b32 s2, s88
	s_mov_b32 s3, s89
	s_waitcnt vmcnt(0)
	v_pk_fma_f32 v[126:127], v[126:127], v[134:135], v[138:139]
	v_pk_fma_f32 v[128:129], v[128:129], v[136:137], v[140:141]
	v_pk_fma_f32 v[122:123], v[122:123], v[130:131], v[142:143]
	v_pk_fma_f32 v[124:125], v[124:125], v[132:133], v[144:145]
	v_pk_fma_f32 v[118:119], v[118:119], v[134:135], v[146:147]
	v_pk_fma_f32 v[120:121], v[120:121], v[136:137], v[148:149]
	v_pk_fma_f32 v[114:115], v[114:115], v[130:131], v[150:151]
	v_pk_fma_f32 v[116:117], v[116:117], v[132:133], v[152:153]
	v_pk_fma_f32 v[110:111], v[110:111], v[134:135], v[154:155]
	v_pk_fma_f32 v[112:113], v[112:113], v[136:137], v[156:157]
	v_pk_fma_f32 v[106:107], v[106:107], v[130:131], v[158:159]
	v_pk_fma_f32 v[108:109], v[108:109], v[132:133], v[160:161]
	v_pk_fma_f32 v[102:103], v[102:103], v[134:135], v[162:163]
	v_pk_fma_f32 v[104:105], v[104:105], v[136:137], v[164:165]
	v_pk_fma_f32 v[98:99], v[98:99], v[130:131], v[166:167]
	v_pk_fma_f32 v[100:101], v[100:101], v[132:133], v[168:169]
	v_pk_fma_f32 v[94:95], v[94:95], v[134:135], v[186:187]
	v_pk_fma_f32 v[96:97], v[96:97], v[136:137], v[188:189]
	v_pk_fma_f32 v[90:91], v[90:91], v[130:131], v[190:191]
	v_pk_fma_f32 v[92:93], v[92:93], v[132:133], v[192:193]
	v_pk_fma_f32 v[86:87], v[86:87], v[134:135], v[194:195]
	v_pk_fma_f32 v[88:89], v[88:89], v[136:137], v[196:197]
	v_pk_fma_f32 v[82:83], v[82:83], v[130:131], v[198:199]
	v_pk_fma_f32 v[84:85], v[84:85], v[132:133], v[200:201]
	v_pk_fma_f32 v[78:79], v[78:79], v[134:135], v[226:227]
	v_pk_fma_f32 v[80:81], v[80:81], v[136:137], v[228:229]
	v_pk_fma_f32 v[74:75], v[74:75], v[130:131], v[230:231]
	v_pk_fma_f32 v[76:77], v[76:77], v[132:133], v[232:233]
	v_pk_fma_f32 v[70:71], v[70:71], v[134:135], v[234:235]
	v_pk_fma_f32 v[72:73], v[72:73], v[136:137], v[236:237]
	v_pk_fma_f32 v[66:67], v[66:67], v[130:131], v[242:243]
	v_pk_fma_f32 v[68:69], v[68:69], v[132:133], v[244:245]
	s_cmp_lg_u32 s13, 0
	s_cbranch_scc1 .Lre0_done
	global_store_dwordx4 v178, v[126:129], s[2:3] offset:0
	global_store_dwordx4 v178, v[122:125], s[2:3] offset:64
	s_add_u32 s2, s2, 0x10000
	s_addc_u32 s3, s3, 0
	global_store_dwordx4 v178, v[118:121], s[2:3] offset:0
	global_store_dwordx4 v178, v[114:117], s[2:3] offset:64
	s_add_u32 s2, s2, 0x10000
	s_addc_u32 s3, s3, 0
	global_store_dwordx4 v178, v[110:113], s[2:3] offset:0
	global_store_dwordx4 v178, v[106:109], s[2:3] offset:64
	s_add_u32 s2, s2, 0x10000
	s_addc_u32 s3, s3, 0
	global_store_dwordx4 v178, v[102:105], s[2:3] offset:0
	global_store_dwordx4 v178, v[98:101], s[2:3] offset:64
	s_add_u32 s2, s2, 0x50000
	s_addc_u32 s3, s3, 0
	global_store_dwordx4 v178, v[94:97], s[2:3] offset:0
	global_store_dwordx4 v178, v[90:93], s[2:3] offset:64
	s_add_u32 s2, s2, 0x10000
	s_addc_u32 s3, s3, 0
	global_store_dwordx4 v178, v[86:89], s[2:3] offset:0
	global_store_dwordx4 v178, v[82:85], s[2:3] offset:64
	s_add_u32 s2, s2, 0x10000
	s_addc_u32 s3, s3, 0
	global_store_dwordx4 v178, v[78:81], s[2:3] offset:0
	global_store_dwordx4 v178, v[74:77], s[2:3] offset:64
	s_add_u32 s2, s2, 0x10000
	s_addc_u32 s3, s3, 0
	global_store_dwordx4 v178, v[70:73], s[2:3] offset:0
	global_store_dwordx4 v178, v[66:69], s[2:3] offset:64
	s_branch .Lre0_done

.Lre0_done:
	global_load_dwordx4 v[134:137], v0, s[42:43] offset:512
	global_load_dwordx4 v[130:133], v0, s[42:43] offset:576
	s_and_b64 vcc, exec, s[34:35]
	s_cbranch_vccz .Lre1_split
	s_add_u32 s2, s88, s22
	s_addc_u32 s3, s89, s23
	s_nop 1
	global_load_dwordx4 v[138:141], v178, s[2:3] offset:512
	global_load_dwordx4 v[142:145], v178, s[2:3] offset:576
	s_add_u32 s2, s2, 0x10000
	s_addc_u32 s3, s3, 0
	global_load_dwordx4 v[146:149], v178, s[2:3] offset:512
	global_load_dwordx4 v[150:153], v178, s[2:3] offset:576
	s_add_u32 s2, s2, 0x10000
	s_addc_u32 s3, s3, 0
	global_load_dwordx4 v[154:157], v178, s[2:3] offset:512
	global_load_dwordx4 v[158:161], v178, s[2:3] offset:576
	s_add_u32 s2, s2, 0x10000
	s_addc_u32 s3, s3, 0
	global_load_dwordx4 v[162:165], v178, s[2:3] offset:512
	global_load_dwordx4 v[166:169], v178, s[2:3] offset:576
	s_add_u32 s2, s2, 0x50000
	s_addc_u32 s3, s3, 0
	global_load_dwordx4 v[186:189], v178, s[2:3] offset:512
	global_load_dwordx4 v[190:193], v178, s[2:3] offset:576
	s_add_u32 s2, s2, 0x10000
	s_addc_u32 s3, s3, 0
	global_load_dwordx4 v[194:197], v178, s[2:3] offset:512
	global_load_dwordx4 v[198:201], v178, s[2:3] offset:576
	s_add_u32 s2, s2, 0x10000
	s_addc_u32 s3, s3, 0
	global_load_dwordx4 v[226:229], v178, s[2:3] offset:512
	global_load_dwordx4 v[230:233], v178, s[2:3] offset:576
	s_add_u32 s2, s2, 0x10000
	s_addc_u32 s3, s3, 0
	global_load_dwordx4 v[234:237], v178, s[2:3] offset:512
	global_load_dwordx4 v[242:245], v178, s[2:3] offset:576
	s_mov_b32 s2, s88
	s_mov_b32 s3, s89
	s_waitcnt vmcnt(0)
	v_pk_fma_f32 v[62:63], v[62:63], v[134:135], v[138:139]
	v_pk_fma_f32 v[64:65], v[64:65], v[136:137], v[140:141]
	v_pk_fma_f32 v[58:59], v[58:59], v[130:131], v[142:143]
	v_pk_fma_f32 v[60:61], v[60:61], v[132:133], v[144:145]
	v_pk_fma_f32 v[54:55], v[54:55], v[134:135], v[146:147]
	v_pk_fma_f32 v[56:57], v[56:57], v[136:137], v[148:149]
	v_pk_fma_f32 v[50:51], v[50:51], v[130:131], v[150:151]
	v_pk_fma_f32 v[52:53], v[52:53], v[132:133], v[152:153]
	v_pk_fma_f32 v[46:47], v[46:47], v[134:135], v[154:155]
	v_pk_fma_f32 v[48:49], v[48:49], v[136:137], v[156:157]
	v_pk_fma_f32 v[42:43], v[42:43], v[130:131], v[158:159]
	v_pk_fma_f32 v[44:45], v[44:45], v[132:133], v[160:161]
	v_pk_fma_f32 v[38:39], v[38:39], v[134:135], v[162:163]
	v_pk_fma_f32 v[40:41], v[40:41], v[136:137], v[164:165]
	v_pk_fma_f32 v[34:35], v[34:35], v[130:131], v[166:167]
	v_pk_fma_f32 v[36:37], v[36:37], v[132:133], v[168:169]
	v_pk_fma_f32 v[30:31], v[30:31], v[134:135], v[186:187]
	v_pk_fma_f32 v[32:33], v[32:33], v[136:137], v[188:189]
	v_pk_fma_f32 v[26:27], v[26:27], v[130:131], v[190:191]
	v_pk_fma_f32 v[28:29], v[28:29], v[132:133], v[192:193]
	v_pk_fma_f32 v[22:23], v[22:23], v[134:135], v[194:195]
	v_pk_fma_f32 v[24:25], v[24:25], v[136:137], v[196:197]
	v_pk_fma_f32 v[18:19], v[18:19], v[130:131], v[198:199]
	v_pk_fma_f32 v[20:21], v[20:21], v[132:133], v[200:201]
	v_pk_fma_f32 v[14:15], v[14:15], v[134:135], v[226:227]
	v_pk_fma_f32 v[16:17], v[16:17], v[136:137], v[228:229]
	v_pk_fma_f32 v[10:11], v[10:11], v[130:131], v[230:231]
	v_pk_fma_f32 v[12:13], v[12:13], v[132:133], v[232:233]
	v_pk_fma_f32 v[6:7], v[6:7], v[134:135], v[234:235]
	v_pk_fma_f32 v[8:9], v[8:9], v[136:137], v[236:237]
	v_pk_fma_f32 v[2:3], v[2:3], v[130:131], v[242:243]
	v_pk_fma_f32 v[4:5], v[4:5], v[132:133], v[244:245]
	s_cmp_lg_u32 s13, 0
	s_cbranch_scc1 .Lre1_done
	global_store_dwordx4 v178, v[62:65], s[2:3] offset:512
	global_store_dwordx4 v178, v[58:61], s[2:3] offset:576
	s_add_u32 s2, s2, 0x10000
	s_addc_u32 s3, s3, 0
	global_store_dwordx4 v178, v[54:57], s[2:3] offset:512
	global_store_dwordx4 v178, v[50:53], s[2:3] offset:576
	s_add_u32 s2, s2, 0x10000
	s_addc_u32 s3, s3, 0
	global_store_dwordx4 v178, v[46:49], s[2:3] offset:512
	global_store_dwordx4 v178, v[42:45], s[2:3] offset:576
	s_add_u32 s2, s2, 0x10000
	s_addc_u32 s3, s3, 0
	global_store_dwordx4 v178, v[38:41], s[2:3] offset:512
	global_store_dwordx4 v178, v[34:37], s[2:3] offset:576
	s_add_u32 s2, s2, 0x50000
	s_addc_u32 s3, s3, 0
	global_store_dwordx4 v178, v[30:33], s[2:3] offset:512
	global_store_dwordx4 v178, v[26:29], s[2:3] offset:576
	s_add_u32 s2, s2, 0x10000
	s_addc_u32 s3, s3, 0
	global_store_dwordx4 v178, v[22:25], s[2:3] offset:512
	global_store_dwordx4 v178, v[18:21], s[2:3] offset:576
	s_add_u32 s2, s2, 0x10000
	s_addc_u32 s3, s3, 0
	global_store_dwordx4 v178, v[14:17], s[2:3] offset:512
	global_store_dwordx4 v178, v[10:13], s[2:3] offset:576
	s_add_u32 s2, s2, 0x10000
	s_addc_u32 s3, s3, 0
	global_store_dwordx4 v178, v[6:9], s[2:3] offset:512
	global_store_dwordx4 v178, v[2:5], s[2:3] offset:576
	s_branch .Lre1_done

.Lre1_done:
	s_cmp_lg_u32 s13, 0
	s_cbranch_scc0 .Lfz_skip
	s_cmpk_gt_u32 s49, 0xff
	s_cbranch_scc1 .Lfz_al
	s_barrier
.Lfz_al:
	v_readlane_b32 s3, v255, 14
	v_readlane_b32 s2, v255, 12
	s_cmp_eq_u32 s3, 5
	s_cselect_b32 s44, 0, 1
	s_add_i32 s2, s2, s44
	v_readlane_b32 s12, v254, 21
	v_readlane_b32 s13, v254, 22
	v_readlane_b32 s42, v254, 54
	v_readlane_b32 s43, v254, 55
	s_cmp_eq_u32 s3, 5
	s_cselect_b32 s12, s12, s42
	s_cselect_b32 s13, s13, s43
	s_cselect_b32 s3, 0x3000, 0
	s_lshr_b32 s44, s49, 6
	s_and_b32 s44, s44, 3
	s_lshl_b32 s44, s44, 7
	s_lshl_b32 s45, s87, 10
	s_add_i32 s44, s44, s45
	s_lshl_b32 s45, s2, 12
	s_add_i32 s45, s45, s44
	s_add_u32 s12, s12, s45
	s_addc_u32 s13, s13, 0
	v_readlane_b32 s42, v252, 11
	v_readlane_b32 s43, v252, 12
	s_mul_i32 s45, s2, 0xc000
	s_add_i32 s45, s45, s3
	s_add_i32 s45, s45, s44
	s_add_u32 s42, s42, s45
	s_addc_u32 s43, s43, 0
	s_add_u32 s44, s42, 0x1000
	s_addc_u32 s45, s43, 0
	v_lshlrev_b32_e32 v180, 4, v179
	s_nop 1
	global_load_dwordx4 v[130:133], v180, s[12:13]
	global_load_dwordx4 v[146:149], v180, s[44:45]
	global_load_dwordx4 v[186:189], v180, s[42:43]
	global_load_dwordx4 v[134:137], v180, s[12:13] offset:64
	global_load_dwordx4 v[150:153], v180, s[44:45] offset:64
	global_load_dwordx4 v[190:193], v180, s[42:43] offset:64
	global_load_dwordx4 v[138:141], v180, s[12:13] offset:512
	global_load_dwordx4 v[154:157], v180, s[44:45] offset:512
	global_load_dwordx4 v[194:197], v180, s[42:43] offset:512
	global_load_dwordx4 v[142:145], v180, s[12:13] offset:576
	global_load_dwordx4 v[158:161], v180, s[44:45] offset:576
	global_load_dwordx4 v[198:201], v180, s[42:43] offset:576
	v_mul_f32_e32 v226, v126, v126
	v_fmac_f32_e32 v226, v127, v127
	v_fmac_f32_e32 v226, v128, v128
	v_fmac_f32_e32 v226, v129, v129
	v_fmac_f32_e32 v226, v122, v122
	v_fmac_f32_e32 v226, v123, v123
	v_fmac_f32_e32 v226, v124, v124
	v_fmac_f32_e32 v226, v125, v125
	v_fmac_f32_e32 v226, v62, v62
	v_fmac_f32_e32 v226, v63, v63
	v_fmac_f32_e32 v226, v64, v64
	v_fmac_f32_e32 v226, v65, v65
	v_fmac_f32_e32 v226, v58, v58
	v_fmac_f32_e32 v226, v59, v59
	v_fmac_f32_e32 v226, v60, v60
	v_fmac_f32_e32 v226, v61, v61
	v_mul_f32_e32 v227, v118, v118
	v_fmac_f32_e32 v227, v119, v119
	v_fmac_f32_e32 v227, v120, v120
	v_fmac_f32_e32 v227, v121, v121
	v_fmac_f32_e32 v227, v114, v114
	v_fmac_f32_e32 v227, v115, v115
	v_fmac_f32_e32 v227, v116, v116
	v_fmac_f32_e32 v227, v117, v117
	v_fmac_f32_e32 v227, v54, v54
	v_fmac_f32_e32 v227, v55, v55
	v_fmac_f32_e32 v227, v56, v56
	v_fmac_f32_e32 v227, v57, v57
	v_fmac_f32_e32 v227, v50, v50
	v_fmac_f32_e32 v227, v51, v51
	v_fmac_f32_e32 v227, v52, v52
	v_fmac_f32_e32 v227, v53, v53
	v_mul_f32_e32 v228, v110, v110
	v_fmac_f32_e32 v228, v111, v111
	v_fmac_f32_e32 v228, v112, v112
	v_fmac_f32_e32 v228, v113, v113
	v_fmac_f32_e32 v228, v106, v106
	v_fmac_f32_e32 v228, v107, v107
	v_fmac_f32_e32 v228, v108, v108
	v_fmac_f32_e32 v228, v109, v109
	v_fmac_f32_e32 v228, v46, v46
	v_fmac_f32_e32 v228, v47, v47
	v_fmac_f32_e32 v228, v48, v48
	v_fmac_f32_e32 v228, v49, v49
	v_fmac_f32_e32 v228, v42, v42
	v_fmac_f32_e32 v228, v43, v43
	v_fmac_f32_e32 v228, v44, v44
	v_fmac_f32_e32 v228, v45, v45
	v_mul_f32_e32 v229, v102, v102
	v_fmac_f32_e32 v229, v103, v103
	v_fmac_f32_e32 v229, v104, v104
	v_fmac_f32_e32 v229, v105, v105
	v_fmac_f32_e32 v229, v98, v98
	v_fmac_f32_e32 v229, v99, v99
	v_fmac_f32_e32 v229, v100, v100
	v_fmac_f32_e32 v229, v101, v101
	v_fmac_f32_e32 v229, v38, v38
	v_fmac_f32_e32 v229, v39, v39
	v_fmac_f32_e32 v229, v40, v40
	v_fmac_f32_e32 v229, v41, v41
	v_fmac_f32_e32 v229, v34, v34
	v_fmac_f32_e32 v229, v35, v35
	v_fmac_f32_e32 v229, v36, v36
	v_fmac_f32_e32 v229, v37, v37
	v_mul_f32_e32 v230, v94, v94
	v_fmac_f32_e32 v230, v95, v95
	v_fmac_f32_e32 v230, v96, v96
	v_fmac_f32_e32 v230, v97, v97
	v_fmac_f32_e32 v230, v90, v90
	v_fmac_f32_e32 v230, v91, v91
	v_fmac_f32_e32 v230, v92, v92
	v_fmac_f32_e32 v230, v93, v93
	v_fmac_f32_e32 v230, v30, v30
	v_fmac_f32_e32 v230, v31, v31
	v_fmac_f32_e32 v230, v32, v32
	v_fmac_f32_e32 v230, v33, v33
	v_fmac_f32_e32 v230, v26, v26
	v_fmac_f32_e32 v230, v27, v27
	v_fmac_f32_e32 v230, v28, v28
	v_fmac_f32_e32 v230, v29, v29
	v_mul_f32_e32 v231, v86, v86
	v_fmac_f32_e32 v231, v87, v87
	v_fmac_f32_e32 v231, v88, v88
	v_fmac_f32_e32 v231, v89, v89
	v_fmac_f32_e32 v231, v82, v82
	v_fmac_f32_e32 v231, v83, v83
	v_fmac_f32_e32 v231, v84, v84
	v_fmac_f32_e32 v231, v85, v85
	v_fmac_f32_e32 v231, v22, v22
	v_fmac_f32_e32 v231, v23, v23
	v_fmac_f32_e32 v231, v24, v24
	v_fmac_f32_e32 v231, v25, v25
	v_fmac_f32_e32 v231, v18, v18
	v_fmac_f32_e32 v231, v19, v19
	v_fmac_f32_e32 v231, v20, v20
	v_fmac_f32_e32 v231, v21, v21
	v_mul_f32_e32 v232, v78, v78
	v_fmac_f32_e32 v232, v79, v79
	v_fmac_f32_e32 v232, v80, v80
	v_fmac_f32_e32 v232, v81, v81
	v_fmac_f32_e32 v232, v74, v74
	v_fmac_f32_e32 v232, v75, v75
	v_fmac_f32_e32 v232, v76, v76
	v_fmac_f32_e32 v232, v77, v77
	v_fmac_f32_e32 v232, v14, v14
	v_fmac_f32_e32 v232, v15, v15
	v_fmac_f32_e32 v232, v16, v16
	v_fmac_f32_e32 v232, v17, v17
	v_fmac_f32_e32 v232, v10, v10
	v_fmac_f32_e32 v232, v11, v11
	v_fmac_f32_e32 v232, v12, v12
	v_fmac_f32_e32 v232, v13, v13
	v_mul_f32_e32 v233, v70, v70
	v_fmac_f32_e32 v233, v71, v71
	v_fmac_f32_e32 v233, v72, v72
	v_fmac_f32_e32 v233, v73, v73
	v_fmac_f32_e32 v233, v66, v66
	v_fmac_f32_e32 v233, v67, v67
	v_fmac_f32_e32 v233, v68, v68
	v_fmac_f32_e32 v233, v69, v69
	v_fmac_f32_e32 v233, v6, v6
	v_fmac_f32_e32 v233, v7, v7
	v_fmac_f32_e32 v233, v8, v8
	v_fmac_f32_e32 v233, v9, v9
	v_fmac_f32_e32 v233, v2, v2
	v_fmac_f32_e32 v233, v3, v3
	v_fmac_f32_e32 v233, v4, v4
	v_fmac_f32_e32 v233, v5, v5
	v_mov_b32_e32 v234, v226
	v_mov_b32_e32 v235, v227
	v_mov_b32_e32 v236, v228
	v_mov_b32_e32 v237, v229
	v_mov_b32_e32 v242, v230
	v_mov_b32_e32 v243, v231
	v_mov_b32_e32 v244, v232
	v_mov_b32_e32 v245, v233
	v_permlane32_swap_b32_e32 v226, v234
	v_permlane32_swap_b32_e32 v227, v235
	v_permlane32_swap_b32_e32 v228, v236
	v_permlane32_swap_b32_e32 v229, v237
	v_permlane32_swap_b32_e32 v230, v242
	v_permlane32_swap_b32_e32 v231, v243
	v_permlane32_swap_b32_e32 v232, v244
	v_permlane32_swap_b32_e32 v233, v245
	v_add_f32_e32 v226, v226, v234
	v_add_f32_e32 v227, v227, v235
	v_add_f32_e32 v228, v228, v236
	v_add_f32_e32 v229, v229, v237
	v_add_f32_e32 v230, v230, v242
	v_add_f32_e32 v231, v231, v243
	v_add_f32_e32 v232, v232, v244
	v_add_f32_e32 v233, v233, v245
	v_mov_b32_e32 v234, v226
	v_mov_b32_e32 v235, v227
	v_mov_b32_e32 v236, v228
	v_mov_b32_e32 v237, v229
	v_mov_b32_e32 v242, v230
	v_mov_b32_e32 v243, v231
	v_mov_b32_e32 v244, v232
	v_mov_b32_e32 v245, v233
	v_permlane16_swap_b32_e32 v226, v234
	v_permlane16_swap_b32_e32 v227, v235
	v_permlane16_swap_b32_e32 v228, v236
	v_permlane16_swap_b32_e32 v229, v237
	v_permlane16_swap_b32_e32 v230, v242
	v_permlane16_swap_b32_e32 v231, v243
	v_permlane16_swap_b32_e32 v232, v244
	v_permlane16_swap_b32_e32 v233, v245
	v_add_f32_e32 v226, v226, v234
	v_add_f32_e32 v227, v227, v235
	v_add_f32_e32 v228, v228, v236
	v_add_f32_e32 v229, v229, v237
	v_add_f32_e32 v230, v230, v242
	v_add_f32_e32 v231, v231, v243
	v_add_f32_e32 v232, v232, v244
	v_add_f32_e32 v233, v233, v245
	s_lshr_b32 s2, s49, 6
	s_and_b32 s3, s2, 3
	s_lshr_b32 s2, s2, 2
	s_lshl_b32 s2, s2, 10
	s_lshl_b32 s3, s3, 2
	s_add_i32 s2, s2, s3
	s_add_i32 s2, s2, 0x21400
	v_and_b32_e32 v181, 15, v202
	v_lshl_add_u32 v181, v181, 4, s2
	s_mov_b64 s[34:35], exec
	s_mov_b64 exec, 0xffff
	ds_write_b32 v181, v226
	ds_write_b32 v181, v227 offset:256
	ds_write_b32 v181, v228 offset:512
	ds_write_b32 v181, v229 offset:768
	ds_write_b32 v181, v230 offset:2048
	ds_write_b32 v181, v231 offset:2304
	ds_write_b32 v181, v232 offset:2560
	ds_write_b32 v181, v233 offset:2816
	s_mov_b64 exec, s[34:35]
	s_cmpk_gt_u32 s49, 0xff
	s_cbranch_scc0 .Lfz_w03a
	s_mov_b32 s2, s88
	s_mov_b32 s3, s89
	global_store_dwordx4 v178, v[126:129], s[2:3] offset:0
	global_store_dwordx4 v178, v[122:125], s[2:3] offset:64
	s_add_u32 s2, s2, 0x10000
	s_addc_u32 s3, s3, 0
	global_store_dwordx4 v178, v[118:121], s[2:3] offset:0
	global_store_dwordx4 v178, v[114:117], s[2:3] offset:64
	s_add_u32 s2, s2, 0x10000
	s_addc_u32 s3, s3, 0
	global_store_dwordx4 v178, v[110:113], s[2:3] offset:0
	global_store_dwordx4 v178, v[106:109], s[2:3] offset:64
	s_add_u32 s2, s2, 0x10000
	s_addc_u32 s3, s3, 0
	global_store_dwordx4 v178, v[102:105], s[2:3] offset:0
	global_store_dwordx4 v178, v[98:101], s[2:3] offset:64
	s_add_u32 s2, s2, 0x50000
	s_addc_u32 s3, s3, 0
	global_store_dwordx4 v178, v[94:97], s[2:3] offset:0
	global_store_dwordx4 v178, v[90:93], s[2:3] offset:64
	s_add_u32 s2, s2, 0x10000
	s_addc_u32 s3, s3, 0
	global_store_dwordx4 v178, v[86:89], s[2:3] offset:0
	global_store_dwordx4 v178, v[82:85], s[2:3] offset:64
	s_add_u32 s2, s2, 0x10000
	s_addc_u32 s3, s3, 0
	global_store_dwordx4 v178, v[78:81], s[2:3] offset:0
	global_store_dwordx4 v178, v[74:77], s[2:3] offset:64
	s_add_u32 s2, s2, 0x10000
	s_addc_u32 s3, s3, 0
	global_store_dwordx4 v178, v[70:73], s[2:3] offset:0
	global_store_dwordx4 v178, v[66:69], s[2:3] offset:64
	s_mov_b32 s2, s88
	s_mov_b32 s3, s89
	global_store_dwordx4 v178, v[62:65], s[2:3] offset:512
	global_store_dwordx4 v178, v[58:61], s[2:3] offset:576
	s_add_u32 s2, s2, 0x10000
	s_addc_u32 s3, s3, 0
	global_store_dwordx4 v178, v[54:57], s[2:3] offset:512
	global_store_dwordx4 v178, v[50:53], s[2:3] offset:576
	s_add_u32 s2, s2, 0x10000
	s_addc_u32 s3, s3, 0
	global_store_dwordx4 v178, v[46:49], s[2:3] offset:512
	global_store_dwordx4 v178, v[42:45], s[2:3] offset:576
	s_add_u32 s2, s2, 0x10000
	s_addc_u32 s3, s3, 0
	global_store_dwordx4 v178, v[38:41], s[2:3] offset:512
	global_store_dwordx4 v178, v[34:37], s[2:3] offset:576
	s_add_u32 s2, s2, 0x50000
	s_addc_u32 s3, s3, 0
	global_store_dwordx4 v178, v[30:33], s[2:3] offset:512
	global_store_dwordx4 v178, v[26:29], s[2:3] offset:576
	s_add_u32 s2, s2, 0x10000
	s_addc_u32 s3, s3, 0
	global_store_dwordx4 v178, v[22:25], s[2:3] offset:512
	global_store_dwordx4 v178, v[18:21], s[2:3] offset:576
	s_add_u32 s2, s2, 0x10000
	s_addc_u32 s3, s3, 0
	global_store_dwordx4 v178, v[14:17], s[2:3] offset:512
	global_store_dwordx4 v178, v[10:13], s[2:3] offset:576
	s_add_u32 s2, s2, 0x10000
	s_addc_u32 s3, s3, 0
	global_store_dwordx4 v178, v[6:9], s[2:3] offset:512
	global_store_dwordx4 v178, v[2:5], s[2:3] offset:576
	s_waitcnt vmcnt(32) lgkmcnt(0)
	s_branch .Lfz_b1
.Lfz_w03a:
	s_waitcnt vmcnt(0) lgkmcnt(0)
.Lfz_b1:
	s_barrier
	v_add_f32_e32 v146, 1.0, v146
	v_add_f32_e32 v147, 1.0, v147
	v_add_f32_e32 v148, 1.0, v148
	v_add_f32_e32 v149, 1.0, v149
	v_add_f32_e32 v150, 1.0, v150
	v_add_f32_e32 v151, 1.0, v151
	v_add_f32_e32 v152, 1.0, v152
	v_add_f32_e32 v153, 1.0, v153
	v_add_f32_e32 v154, 1.0, v154
	v_add_f32_e32 v155, 1.0, v155
	v_add_f32_e32 v156, 1.0, v156
	v_add_f32_e32 v157, 1.0, v157
	v_add_f32_e32 v158, 1.0, v158
	v_add_f32_e32 v159, 1.0, v159
	v_add_f32_e32 v160, 1.0, v160
	v_add_f32_e32 v161, 1.0, v161
	v_mul_f32_e32 v130, v130, v146
	v_mul_f32_e32 v131, v131, v147
	v_mul_f32_e32 v132, v132, v148
	v_mul_f32_e32 v133, v133, v149
	v_mul_f32_e32 v134, v134, v150
	v_mul_f32_e32 v135, v135, v151
	v_mul_f32_e32 v136, v136, v152
	v_mul_f32_e32 v137, v137, v153
	v_mul_f32_e32 v138, v138, v154
	v_mul_f32_e32 v139, v139, v155
	v_mul_f32_e32 v140, v140, v156
	v_mul_f32_e32 v141, v141, v157
	v_mul_f32_e32 v142, v142, v158
	v_mul_f32_e32 v143, v143, v159
	v_mul_f32_e32 v144, v144, v160
	v_mul_f32_e32 v145, v145, v161
	s_lshl_b32 s2, s86, 12
	s_add_u32 s2, s8, s2
	s_addc_u32 s3, s9, 0
	s_add_u32 s2, s2, 0x15234000
	s_addc_u32 s3, s3, 0
	s_lshl_b32 s12, s87, 10
	s_add_u32 s12, s2, s12
	s_addc_u32 s13, s3, 0
	s_lshl_b32 s42, s86, 5
	s_add_u32 s42, s8, s42
	s_addc_u32 s43, s9, 0
	s_add_u32 s42, s42, 0x3600
	s_addc_u32 s43, s43, 0
	s_cmpk_gt_u32 s49, 0xff
	s_cbranch_scc1 .Lfz_p1
	s_movk_i32 s44, 0x1400
	s_add_i32 s44, s44, 0x20000
	v_lshl_add_u32 v154, v202, 4, s44
	v_lshlrev_b32_e32 v155, 2, v202
	ds_read_b128 v[146:149], v154
	s_waitcnt lgkmcnt(0)
	v_add_f32_e32 v146, v146, v147
	v_add_f32_e32 v148, v148, v149
	v_add_f32_e32 v146, v146, v148
	global_store_dword v155, v146, s[12:13] sc0 sc1
	s_waitcnt vmcnt(0)
.Lfz_p1:
	s_barrier
	s_cmpk_lt_u32 s49, 64
	s_cbranch_scc0 .Lfz_arr
	s_mov_b64 s[34:35], exec
	s_mov_b64 exec, 1
	v_mov_b32_e32 v158, 0
	v_mov_b32_e32 v159, 1
	global_atomic_add v158, v159, s[42:43]
	v_readlane_b32 s44, v255, 14
	v_readlane_b32 s45, v255, 12
	s_cmp_eq_u32 s44, 5
	s_cselect_b32 s44, 0, 1
	s_lshl_b32 s45, s45, 1
	s_add_i32 s45, s45, s44
	s_add_i32 s45, s45, 1
	s_lshl_b32 vcc_lo, s45, 2
	s_mov_b32 s44, 0
.Lfz_poll:
	global_load_dword v159, v158, s[42:43] sc1
	s_waitcnt vmcnt(0)
	v_readfirstlane_b32 s45, v159
	s_cmp_ge_u32 s45, vcc_lo
	s_cbranch_scc1 .Lfz_polled
	s_add_i32 s44, s44, 1
	s_cmp_lt_u32 s44, 0x4000
	s_cbranch_scc0 .Lfz_polled
	s_sleep 1
	s_branch .Lfz_poll

.Lfz_arr:
	s_barrier
	s_cmpk_gt_u32 s49, 0xff
	s_cbranch_scc1 .Lfz_p2
	global_load_dword v146, v155, s[2:3] sc0 sc1
	global_load_dword v147, v155, s[2:3] offset:1024 sc0 sc1
	global_load_dword v148, v155, s[2:3] offset:2048 sc0 sc1
	global_load_dword v149, v155, s[2:3] offset:3072 sc0 sc1
	v_mov_b32_e32 v150, 0x3a800000
	s_movk_i32 s44, 0x2400
	s_add_i32 s44, s44, 0x20000
	v_add_u32_e32 v151, s44, v155
	s_waitcnt vmcnt(0)
	v_add_f32_e32 v146, v146, v147
	v_add_f32_e32 v148, v148, v149
	v_add_f32_e32 v146, v146, v148
	v_fma_f32 v146, v146, v150, v203
	v_rsq_f32_e32 v146, v146
	s_nop 0
	ds_write_b32 v151, v146
	s_mov_b32 s2, s88
	s_mov_b32 s3, s89
	global_store_dwordx4 v178, v[126:129], s[2:3] offset:0
	global_store_dwordx4 v178, v[122:125], s[2:3] offset:64
	s_add_u32 s2, s2, 0x10000
	s_addc_u32 s3, s3, 0
	global_store_dwordx4 v178, v[118:121], s[2:3] offset:0
	global_store_dwordx4 v178, v[114:117], s[2:3] offset:64
	s_add_u32 s2, s2, 0x10000
	s_addc_u32 s3, s3, 0
	global_store_dwordx4 v178, v[110:113], s[2:3] offset:0
	global_store_dwordx4 v178, v[106:109], s[2:3] offset:64
	s_add_u32 s2, s2, 0x10000
	s_addc_u32 s3, s3, 0
	global_store_dwordx4 v178, v[102:105], s[2:3] offset:0
	global_store_dwordx4 v178, v[98:101], s[2:3] offset:64
	s_add_u32 s2, s2, 0x50000
	s_addc_u32 s3, s3, 0
	global_store_dwordx4 v178, v[94:97], s[2:3] offset:0
	global_store_dwordx4 v178, v[90:93], s[2:3] offset:64
	s_add_u32 s2, s2, 0x10000
	s_addc_u32 s3, s3, 0
	global_store_dwordx4 v178, v[86:89], s[2:3] offset:0
	global_store_dwordx4 v178, v[82:85], s[2:3] offset:64
	s_add_u32 s2, s2, 0x10000
	s_addc_u32 s3, s3, 0
	global_store_dwordx4 v178, v[78:81], s[2:3] offset:0
	global_store_dwordx4 v178, v[74:77], s[2:3] offset:64
	s_add_u32 s2, s2, 0x10000
	s_addc_u32 s3, s3, 0
	global_store_dwordx4 v178, v[70:73], s[2:3] offset:0
	global_store_dwordx4 v178, v[66:69], s[2:3] offset:64
	s_mov_b32 s2, s88
	s_mov_b32 s3, s89
	global_store_dwordx4 v178, v[62:65], s[2:3] offset:512
	global_store_dwordx4 v178, v[58:61], s[2:3] offset:576
	s_add_u32 s2, s2, 0x10000
	s_addc_u32 s3, s3, 0
	global_store_dwordx4 v178, v[54:57], s[2:3] offset:512
	global_store_dwordx4 v178, v[50:53], s[2:3] offset:576
	s_add_u32 s2, s2, 0x10000
	s_addc_u32 s3, s3, 0
	global_store_dwordx4 v178, v[46:49], s[2:3] offset:512
	global_store_dwordx4 v178, v[42:45], s[2:3] offset:576
	s_add_u32 s2, s2, 0x10000
	s_addc_u32 s3, s3, 0
	global_store_dwordx4 v178, v[38:41], s[2:3] offset:512
	global_store_dwordx4 v178, v[34:37], s[2:3] offset:576
	s_add_u32 s2, s2, 0x50000
	s_addc_u32 s3, s3, 0
	global_store_dwordx4 v178, v[30:33], s[2:3] offset:512
	global_store_dwordx4 v178, v[26:29], s[2:3] offset:576
	s_add_u32 s2, s2, 0x10000
	s_addc_u32 s3, s3, 0
	global_store_dwordx4 v178, v[22:25], s[2:3] offset:512
	global_store_dwordx4 v178, v[18:21], s[2:3] offset:576
	s_add_u32 s2, s2, 0x10000
	s_addc_u32 s3, s3, 0
	global_store_dwordx4 v178, v[14:17], s[2:3] offset:512
	global_store_dwordx4 v178, v[10:13], s[2:3] offset:576
	s_add_u32 s2, s2, 0x10000
	s_addc_u32 s3, s3, 0
	global_store_dwordx4 v178, v[6:9], s[2:3] offset:512
	global_store_dwordx4 v178, v[2:5], s[2:3] offset:576
	s_waitcnt lgkmcnt(0)
